# phase0b (in-barrier weight conversions) distributed over waves 1-7 so the barrier-protocol wave of each workgroup is free; non-leaders poll the global generation
# baseline (speedup 1.0000x reference)
.LBB0_128:
	s_or_b64 exec, exec, s[0:1]
	v_mov_b32_e32 v1, v218
	s_movk_i32 s0, 0xb80
	v_ashrrev_i32_e32 v27, 6, v1
	s_mul_i32 s98, s2, 7
	s_add_i32 s98, s98, -1
	s_mul_i32 s99, s88, 7
	v_add_u32_e32 v20, s98, v27
	v_cmp_lt_i32_e64 s[100:101], 0, v27
	v_cmp_gt_i32_e32 vcc, s0, v20
	s_nop 3
	s_and_b64 vcc, vcc, s[100:101]
	s_and_saveexec_b64 s[0:1], vcc
	s_cbranch_execz .LBB0_143
	s_movk_i32 s3, 0x4400
	v_mul_lo_u32 v2, v27, s3
	v_add_u32_e32 v6, 0, v2
	v_lshlrev_b32_e32 v2, 4, v1
	v_and_b32_e32 v18, 0x70, v2
	v_lshlrev_b32_e32 v2, 3, v1
	v_and_b32_e32 v2, 56, v2
	v_mul_u32_u24_e32 v7, 0x84, v2
	v_lshlrev_b32_e32 v2, 1, v2
	v_mov_b32_e32 v3, 0
	v_bfe_u32 v21, v1, 3, 3
	v_lshl_add_u64 v[10:11], s[86:87], 0, v[2:3]
	s_mov_b64 s[4:5], 0x2100000
	v_lshl_add_u64 v[4:5], v[10:11], 0, s[4:5]
	v_lshlrev_b32_e32 v2, 2, v21
	s_mov_b64 s[4:5], 0x1400000
	v_add_u32_e32 v28, v6, v18
	v_mul_u32_u24_e32 v29, 0x84, v21
	v_add3_u32 v25, v6, v7, v2
	v_lshl_add_u64 v[6:7], v[10:11], 0, s[4:5]
	s_mov_b64 s[4:5], 0x1200000
	v_lshlrev_b32_e32 v2, 5, v27
	v_lshl_add_u64 v[8:9], v[10:11], 0, s[4:5]
	s_mov_b64 s[4:5], 0x1000000
	v_mov_b32_e32 v19, v3
	v_lshlrev_b32_e32 v26, 5, v20
	v_lshlrev_b32_e32 v2, 1, v27
	v_add_u32_e32 v28, v28, v29
	v_or_b32_e32 v22, 8, v21
	v_or_b32_e32 v23, 16, v21
	v_or_b32_e32 v24, 24, v21
	v_lshl_add_u64 v[10:11], v[10:11], 0, s[4:5]
	v_lshl_add_u64 v[12:13], s[80:81], 0, v[18:19]
	v_lshl_add_u64 v[14:15], s[70:71], 0, v[18:19]
	v_lshl_add_u64 v[16:17], s[28:29], 0, v[18:19]
	v_lshl_add_u64 v[18:19], s[26:27], 0, v[18:19]
	s_lshl_b32 s3, s99, 5
	v_lshlrev_b32_e32 v27, 1, v20
	s_lshl_b32 s12, s99, 1
	s_mov_b64 s[4:5], 0
	s_movk_i32 s13, 0x1ff
	s_movk_i32 s20, 0x3ff
	s_movk_i32 s21, 0x5ff
	v_add_u32_e32 v29, 0x420, v28
	v_add_u32_e32 v30, 0x428, v28
	v_add_u32_e32 v31, 0x840, v28
	v_add_u32_e32 v32, 0x848, v28
	v_add_u32_e32 v33, 0xc60, v28
	v_add_u32_e32 v34, 0xc68, v28
	v_add_u32_e32 v35, 0x1080, v28
	v_add_u32_e32 v36, 0x1088, v28
	v_add_u32_e32 v37, 0x14a0, v28
	v_add_u32_e32 v38, 0x14a8, v28
	v_add_u32_e32 v39, 0x18c0, v28
	v_add_u32_e32 v40, 0x18c8, v28
	v_add_u32_e32 v41, 0x1ce0, v28
	v_add_u32_e32 v42, 0x1ce8, v28
	s_movk_i32 s26, 0xb7f
	s_branch .LBB0_131
.LBB0_130:
	s_or_b64 exec, exec, s[6:7]
	v_add_u32_e32 v20, s99, v20
	v_cmp_lt_i32_e32 vcc, s26, v20
	v_add_u32_e32 v26, s3, v26
	s_or_b64 s[4:5], vcc, s[4:5]
	v_add_u32_e32 v27, s12, v27
	s_andn2_b64 exec, exec, s[4:5]
	s_cbranch_execz .LBB0_143

	.amdhsa_kernel _Z14fwd_megakernel4Args
		.amdhsa_group_segment_fixed_size 0
		.amdhsa_private_segment_fixed_size 0
		.amdhsa_kernarg_size 472
		.amdhsa_user_sgpr_count 2
		.amdhsa_user_sgpr_dispatch_ptr 0
		.amdhsa_user_sgpr_queue_ptr 0
		.amdhsa_user_sgpr_kernarg_segment_ptr 1
		.amdhsa_user_sgpr_dispatch_id 0
		.amdhsa_user_sgpr_kernarg_preload_length 0
		.amdhsa_user_sgpr_kernarg_preload_offset 0
		.amdhsa_user_sgpr_private_segment_size 0
		.amdhsa_uses_dynamic_stack 0
		.amdhsa_enable_private_segment 0
		.amdhsa_system_sgpr_workgroup_id_x 1
		.amdhsa_system_sgpr_workgroup_id_y 0
		.amdhsa_system_sgpr_workgroup_id_z 0
		.amdhsa_system_sgpr_workgroup_info 0
		.amdhsa_system_vgpr_workitem_id 2
		.amdhsa_next_free_vgpr 256
		.amdhsa_next_free_sgpr 102
		.amdhsa_accum_offset 256
		.amdhsa_reserve_vcc 1
		.amdhsa_float_round_mode_32 0
		.amdhsa_float_round_mode_16_64 0
		.amdhsa_float_denorm_mode_32 3
		.amdhsa_float_denorm_mode_16_64 3
		.amdhsa_dx10_clamp 1
		.amdhsa_ieee_mode 1
		.amdhsa_fp16_overflow 0
		.amdhsa_tg_split 0
		.amdhsa_exception_fp_ieee_invalid_op 0
		.amdhsa_exception_fp_denorm_src 0
		.amdhsa_exception_fp_ieee_div_zero 0
		.amdhsa_exception_fp_ieee_overflow 0
		.amdhsa_exception_fp_ieee_underflow 0
		.amdhsa_exception_fp_ieee_inexact 0
		.amdhsa_exception_int_div_zero 0
	.end_amdhsa_kernel

amdhsa.kernels:
  - .agpr_count:     0
    .args:
      - .offset:         0
        .size:           216
        .value_kind:     by_value
      - .offset:         216
        .size:           4
        .value_kind:     hidden_block_count_x
      - .offset:         220
        .size:           4
        .value_kind:     hidden_block_count_y
      - .offset:         224
        .size:           4
        .value_kind:     hidden_block_count_z
      - .offset:         228
        .size:           2
        .value_kind:     hidden_group_size_x
      - .offset:         230
        .size:           2
        .value_kind:     hidden_group_size_y
      - .offset:         232
        .size:           2
        .value_kind:     hidden_group_size_z
      - .offset:         234
        .size:           2
        .value_kind:     hidden_remainder_x
      - .offset:         236
        .size:           2
        .value_kind:     hidden_remainder_y
      - .offset:         238
        .size:           2
        .value_kind:     hidden_remainder_z
      - .offset:         256
        .size:           8
        .value_kind:     hidden_global_offset_x
      - .offset:         264
        .size:           8
        .value_kind:     hidden_global_offset_y
      - .offset:         272
        .size:           8
        .value_kind:     hidden_global_offset_z
      - .offset:         280
        .size:           2
        .value_kind:     hidden_grid_dims
      - .offset:         304
        .size:           8
        .value_kind:     hidden_multigrid_sync_arg
      - .offset:         336
        .size:           4
        .value_kind:     hidden_dynamic_lds_size
    .group_segment_fixed_size: 0
    .kernarg_segment_align: 8
    .kernarg_segment_size: 472
    .language:       OpenCL C
    .language_version:
      - 2
      - 0
    .max_flat_workgroup_size: 512
    .name:           _Z14fwd_megakernel4Args
    .private_segment_fixed_size: 0
    .sgpr_count:     108
    .sgpr_spill_count: 95
    .symbol:         _Z14fwd_megakernel4Args.kd
    .uniform_work_group_size: 1
    .uses_dynamic_stack: false
    .vgpr_count:     256
    .vgpr_spill_count: 0
    .wavefront_size: 64
